# grid barrier: non-leader workgroups poll the top-level generation word directly (skip the per-XCD release hop), on top of the late MLA DMA issue
# baseline (speedup 1.0000x reference)
.LBB0_84:
	s_or_b64 exec, exec, s[4:5]
	v_cvt_f32_u32_e32 v4, v2
	s_waitcnt vmcnt(0)
	v_readfirstlane_b32 s4, v3
	v_sub_u32_e32 v3, 0, v2
	v_rcp_iflag_f32_e32 v4, v4
	v_add_u32_e32 v5, s4, v1
	v_mul_f32_e32 v4, 0x4f7ffffe, v4
	v_cvt_u32_f32_e32 v4, v4
	v_mul_lo_u32 v1, v3, v4
	v_mul_hi_u32 v1, v4, v1
	v_add_u32_e32 v1, v4, v1
	v_mul_hi_u32 v1, v5, v1
	v_mul_lo_u32 v3, v1, v2
	v_sub_u32_e32 v3, v5, v3
	v_add_u32_e32 v4, 1, v1
	v_sub_u32_e32 v6, v3, v2
	v_cmp_ge_u32_e32 vcc, v3, v2
	s_nop 1
	v_cndmask_b32_e32 v1, v1, v4, vcc
	v_cndmask_b32_e32 v3, v3, v6, vcc
	v_add_u32_e32 v4, 1, v1
	v_cmp_ge_u32_e32 vcc, v3, v2
	v_add_u32_e32 v3, 1, v5
	s_nop 0
	v_cndmask_b32_e32 v1, v1, v4, vcc
	v_mul_lo_u32 v4, v2, v1
	v_add_u32_e32 v2, v4, v2
	v_cmp_ne_u32_e32 vcc, v3, v2
	s_and_saveexec_b64 s[4:5], vcc
	s_xor_b64 s[4:5], exec, s[4:5]
	s_cbranch_execz .LBB0_98
	v_readlane_b32 s6, v230, 29
	v_readlane_b32 s7, v230, 30
	s_waitcnt lgkmcnt(0)
	s_nop 3
	global_load_dword v0, v97, s[6:7] sc1
	s_waitcnt vmcnt(0)
	v_cmp_eq_u32_e32 vcc, v0, v1
	s_and_saveexec_b64 s[6:7], vcc
	s_cbranch_execz .LBB0_97
	s_mov_b32 s16, 1
	s_mov_b64 s[8:9], 0
	s_branch .LBB0_88

.LBB0_90:
	v_readlane_b32 s12, v230, 29
	v_readlane_b32 s13, v230, 30
	s_add_i32 s16, s16, 1
	s_mov_b64 s[34:35], -1
	s_nop 2
	global_load_dword v0, v97, s[12:13] sc1
	s_waitcnt vmcnt(0)
	v_cmp_ne_u32_e32 vcc, v0, v1
	s_orn2_b64 s[12:13], vcc, exec
	s_branch .LBB0_87

.LBB0_756:
	s_or_b64 exec, exec, s[4:5]
	v_cvt_f32_u32_e32 v4, v2
	s_waitcnt vmcnt(0)
	v_readfirstlane_b32 s4, v3
	v_sub_u32_e32 v3, 0, v2
	v_rcp_iflag_f32_e32 v4, v4
	v_add_u32_e32 v5, s4, v1
	v_mul_f32_e32 v4, 0x4f7ffffe, v4
	v_cvt_u32_f32_e32 v4, v4
	v_mul_lo_u32 v1, v3, v4
	v_mul_hi_u32 v1, v4, v1
	v_add_u32_e32 v1, v4, v1
	v_mul_hi_u32 v1, v5, v1
	v_mul_lo_u32 v3, v1, v2
	v_sub_u32_e32 v3, v5, v3
	v_add_u32_e32 v4, 1, v1
	v_cmp_ge_u32_e32 vcc, v3, v2
	s_nop 1
	v_cndmask_b32_e32 v1, v1, v4, vcc
	v_sub_u32_e32 v4, v3, v2
	v_cndmask_b32_e32 v3, v3, v4, vcc
	v_add_u32_e32 v4, 1, v1
	v_cmp_ge_u32_e32 vcc, v3, v2
	v_add_u32_e32 v3, 1, v5
	s_nop 0
	v_cndmask_b32_e32 v1, v1, v4, vcc
	v_mul_lo_u32 v4, v2, v1
	v_add_u32_e32 v2, v4, v2
	v_cmp_ne_u32_e32 vcc, v3, v2
	s_and_saveexec_b64 s[4:5], vcc
	s_xor_b64 s[4:5], exec, s[4:5]
	s_cbranch_execz .LBB0_775
	v_readlane_b32 s6, v230, 29
	v_readlane_b32 s7, v230, 30
	s_waitcnt lgkmcnt(0)
	s_nop 3
	global_load_dword v0, v97, s[6:7] sc1
	s_waitcnt vmcnt(0)
	v_cmp_eq_u32_e32 vcc, v0, v1
	s_and_saveexec_b64 s[6:7], vcc
	s_cbranch_execz .LBB0_774
	s_mov_b32 s16, 1
	s_mov_b64 s[8:9], 0
	s_branch .LBB0_760

.LBB0_840:
	s_or_b64 exec, exec, s[6:7]
	v_cvt_f32_u32_e32 v4, v2
	s_waitcnt vmcnt(0)
	v_readfirstlane_b32 s6, v3
	v_sub_u32_e32 v3, 0, v2
	v_rcp_iflag_f32_e32 v4, v4
	v_add_u32_e32 v5, s6, v1
	v_mul_f32_e32 v4, 0x4f7ffffe, v4
	v_cvt_u32_f32_e32 v4, v4
	v_mul_lo_u32 v1, v3, v4
	v_mul_hi_u32 v1, v4, v1
	v_add_u32_e32 v1, v4, v1
	v_mul_hi_u32 v1, v5, v1
	v_mul_lo_u32 v3, v1, v2
	v_sub_u32_e32 v3, v5, v3
	v_add_u32_e32 v4, 1, v1
	v_cmp_ge_u32_e32 vcc, v3, v2
	s_nop 1
	v_cndmask_b32_e32 v1, v1, v4, vcc
	v_sub_u32_e32 v4, v3, v2
	v_cndmask_b32_e32 v3, v3, v4, vcc
	v_add_u32_e32 v4, 1, v1
	v_cmp_ge_u32_e32 vcc, v3, v2
	v_add_u32_e32 v3, 1, v5
	s_nop 0
	v_cndmask_b32_e32 v1, v1, v4, vcc
	v_mul_lo_u32 v4, v2, v1
	v_add_u32_e32 v2, v4, v2
	v_cmp_ne_u32_e32 vcc, v3, v2
	s_and_saveexec_b64 s[6:7], vcc
	s_xor_b64 s[6:7], exec, s[6:7]
	s_cbranch_execz .LBB0_854
	v_readlane_b32 s8, v230, 29
	v_readlane_b32 s9, v230, 30
	s_waitcnt lgkmcnt(0)
	s_nop 3
	global_load_dword v0, v97, s[8:9] sc1
	s_waitcnt vmcnt(0)
	v_cmp_eq_u32_e32 vcc, v0, v1
	s_and_saveexec_b64 s[8:9], vcc
	s_cbranch_execz .LBB0_853
	s_mov_b32 s16, 1
	s_mov_b64 s[10:11], 0
	s_branch .LBB0_844

.LBB0_846:
	v_readlane_b32 s18, v230, 29
	v_readlane_b32 s19, v230, 30
	s_add_i32 s16, s16, 1
	s_mov_b64 s[36:37], -1
	s_nop 2
	global_load_dword v0, v97, s[18:19] sc1
	s_waitcnt vmcnt(0)
	v_cmp_ne_u32_e32 vcc, v0, v1
	s_orn2_b64 s[34:35], vcc, exec
	s_branch .LBB0_843
